# attention output epilogue: the per-column vector is fetched in one batch right after its first piece instead of 16 bytes per step with a full wait after each step (which also waited for the previous s
# speedup vs baseline: 1.0187x; 1.0118x over previous
.LBB0_597:
	s_or_b64 exec, exec, s[30:31]
	s_movk_i32 s30, 0x100
	v_cmp_gt_u32_e32 vcc, s30, v213
	s_waitcnt lgkmcnt(0)
	s_barrier
	s_and_saveexec_b64 s[30:31], vcc
	s_cbranch_execz .LBB0_577
	ds_read_b128 v[66:69], v64
	ds_read_b128 v[70:73], v64 offset:32
	ds_read_b128 v[74:77], v64 offset:64
	ds_read_b128 v[78:81], v64 offset:96
	ds_read_b128 v[82:85], v64 offset:128
	ds_read_b128 v[86:89], v64 offset:160
	ds_read_b128 v[90:93], v64 offset:192
	ds_read_b128 v[94:97], v64 offset:224
	ds_read_b128 v[98:101], v64 offset:256
	ds_read_b128 v[102:105], v64 offset:288
	ds_read_b128 v[106:109], v64 offset:448
	ds_read_b128 v[110:113], v64 offset:480
	ds_read_b128 v[114:117], v64 offset:320
	ds_read_b128 v[118:121], v64 offset:352
	ds_read_b128 v[122:125], v64 offset:384
	ds_read_b128 v[126:129], v64 offset:416
	s_waitcnt lgkmcnt(14)
	v_pk_add_f32 v[48:49], v[48:49], v[66:67]
	v_pk_add_f32 v[50:51], v[50:51], v[68:69]
	v_pk_mul_f32 v[66:67], v[48:49], v[48:49]
	s_waitcnt lgkmcnt(4)
	v_pk_add_f32 v[12:13], v[12:13], v[110:111]
	v_pk_add_f32 v[14:15], v[14:15], v[112:113]
	global_load_dwordx4 v[110:113], v208, s[46:47]
	global_load_dwordx4 v[176:179], v208, s[46:47] offset:32
	global_load_dwordx4 v[180:183], v208, s[46:47] offset:64
	global_load_dwordx4 v[184:187], v208, s[46:47] offset:96
	global_load_dwordx4 v[188:191], v208, s[46:47] offset:128
	global_load_dwordx4 v[192:195], v208, s[46:47] offset:160
	global_load_dwordx4 v[196:199], v208, s[46:47] offset:192
	global_load_dwordx4 v[200:203], v208, s[46:47] offset:224
	global_load_dwordx4 v[204:207], v208, s[46:47] offset:256
	global_load_dwordx4 v[216:219], v208, s[46:47] offset:288
	global_load_dwordx4 v[220:223], v208, s[46:47] offset:320
	global_load_dwordx4 v[224:227], v208, s[46:47] offset:352
	global_load_dwordx4 v[236:239], v208, s[46:47] offset:384
	global_load_dwordx4 v[240:243], v208, s[46:47] offset:416
	global_load_dwordx4 v[244:247], v208, s[46:47] offset:448
	global_load_dwordx4 v[248:251], v208, s[46:47] offset:480
	v_pk_mul_f32 v[68:69], v[50:51], v[50:51]
	v_add_f32_e32 v66, v66, v67
	v_pk_add_f32 v[52:53], v[52:53], v[70:71]
	v_add_f32_e32 v66, v68, v66
	v_pk_mul_f32 v[70:71], v[52:53], v[52:53]
	v_add_f32_e32 v66, v69, v66
	v_pk_add_f32 v[54:55], v[54:55], v[72:73]
	v_add_f32_e32 v66, v70, v66
	v_pk_mul_f32 v[72:73], v[54:55], v[54:55]
	v_add_f32_e32 v66, v71, v66
	v_pk_add_f32 v[56:57], v[56:57], v[74:75]
	v_add_f32_e32 v66, v72, v66
	v_pk_mul_f32 v[74:75], v[56:57], v[56:57]
	v_add_f32_e32 v66, v73, v66
	v_pk_add_f32 v[58:59], v[58:59], v[76:77]
	v_add_f32_e32 v66, v74, v66
	v_pk_mul_f32 v[76:77], v[58:59], v[58:59]
	v_add_f32_e32 v66, v75, v66
	v_pk_add_f32 v[60:61], v[60:61], v[78:79]
	v_add_f32_e32 v66, v76, v66
	v_pk_mul_f32 v[78:79], v[60:61], v[60:61]
	v_add_f32_e32 v66, v77, v66
	v_pk_add_f32 v[62:63], v[62:63], v[80:81]
	v_add_f32_e32 v66, v78, v66
	v_pk_mul_f32 v[80:81], v[62:63], v[62:63]
	v_add_f32_e32 v66, v79, v66
	v_pk_add_f32 v[82:83], v[32:33], v[82:83]
	v_add_f32_e32 v66, v80, v66
	v_pk_mul_f32 v[134:135], v[82:83], v[82:83]
	v_add_f32_e32 v66, v81, v66
	v_pk_add_f32 v[84:85], v[34:35], v[84:85]
	v_add_f32_e32 v66, v134, v66
	v_pk_mul_f32 v[132:133], v[84:85], v[84:85]
	v_add_f32_e32 v66, v135, v66
	v_pk_add_f32 v[86:87], v[36:37], v[86:87]
	v_add_f32_e32 v66, v132, v66
	v_pk_mul_f32 v[136:137], v[86:87], v[86:87]
	v_add_f32_e32 v66, v133, v66
	v_pk_add_f32 v[38:39], v[38:39], v[88:89]
	v_add_f32_e32 v66, v136, v66
	v_pk_mul_f32 v[88:89], v[38:39], v[38:39]
	v_add_f32_e32 v66, v137, v66
	v_pk_add_f32 v[40:41], v[40:41], v[90:91]
	v_add_f32_e32 v66, v88, v66
	v_pk_mul_f32 v[90:91], v[40:41], v[40:41]
	v_add_f32_e32 v66, v89, v66
	v_pk_add_f32 v[42:43], v[42:43], v[92:93]
	v_add_f32_e32 v66, v90, v66
	v_pk_mul_f32 v[92:93], v[42:43], v[42:43]
	v_add_f32_e32 v66, v91, v66
	v_pk_add_f32 v[44:45], v[44:45], v[94:95]
	v_add_f32_e32 v66, v92, v66
	v_pk_mul_f32 v[94:95], v[44:45], v[44:45]
	v_add_f32_e32 v66, v93, v66
	v_pk_add_f32 v[46:47], v[46:47], v[96:97]
	v_add_f32_e32 v66, v94, v66
	v_pk_mul_f32 v[96:97], v[46:47], v[46:47]
	v_add_f32_e32 v66, v95, v66
	v_pk_add_f32 v[98:99], v[16:17], v[98:99]
	v_add_f32_e32 v66, v96, v66
	v_pk_mul_f32 v[138:139], v[98:99], v[98:99]
	v_add_f32_e32 v66, v97, v66
	v_pk_add_f32 v[34:35], v[18:19], v[100:101]
	v_add_f32_e32 v66, v138, v66
	v_pk_mul_f32 v[100:101], v[34:35], v[34:35]
	v_add_f32_e32 v66, v139, v66
	v_pk_add_f32 v[36:37], v[20:21], v[102:103]
	v_add_f32_e32 v66, v100, v66
	v_pk_mul_f32 v[102:103], v[36:37], v[36:37]
	v_add_f32_e32 v66, v101, v66
	v_pk_add_f32 v[32:33], v[22:23], v[104:105]
	v_add_f32_e32 v66, v102, v66
	v_pk_mul_f32 v[104:105], v[32:33], v[32:33]
	v_add_f32_e32 v66, v103, v66
	s_waitcnt lgkmcnt(3)
	v_pk_add_f32 v[22:23], v[26:27], v[116:117]
	v_pk_add_f32 v[26:27], v[24:25], v[114:115]
	v_add_f32_e32 v66, v104, v66
	v_pk_mul_f32 v[114:115], v[26:27], v[26:27]
	v_add_f32_e32 v66, v105, v66
	v_add_f32_e32 v66, v114, v66
	v_pk_mul_f32 v[116:117], v[22:23], v[22:23]
	v_add_f32_e32 v66, v115, v66
	s_waitcnt lgkmcnt(2)
	v_pk_add_f32 v[24:25], v[28:29], v[118:119]
	v_add_f32_e32 v66, v116, v66
	v_pk_mul_f32 v[28:29], v[24:25], v[24:25]
	v_add_f32_e32 v66, v117, v66
	v_pk_add_f32 v[18:19], v[30:31], v[120:121]
	v_add_f32_e32 v28, v28, v66
	v_pk_mul_f32 v[30:31], v[18:19], v[18:19]
	v_add_f32_e32 v28, v29, v28
	s_waitcnt lgkmcnt(1)
	v_pk_add_f32 v[20:21], v[0:1], v[122:123]
	v_add_f32_e32 v28, v30, v28
	v_pk_mul_f32 v[120:121], v[20:21], v[20:21]
	v_add_f32_e32 v28, v31, v28
	v_pk_add_f32 v[16:17], v[2:3], v[124:125]
	v_add_f32_e32 v28, v120, v28
	v_pk_mul_f32 v[118:119], v[16:17], v[16:17]
	v_add_f32_e32 v28, v121, v28
	s_waitcnt lgkmcnt(0)
	v_pk_add_f32 v[2:3], v[6:7], v[128:129]
	v_pk_add_f32 v[6:7], v[4:5], v[126:127]
	v_add_f32_e32 v28, v118, v28
	v_pk_mul_f32 v[124:125], v[6:7], v[6:7]
	v_add_f32_e32 v28, v119, v28
	v_add_f32_e32 v28, v124, v28
	v_pk_mul_f32 v[122:123], v[2:3], v[2:3]
	v_add_f32_e32 v28, v125, v28
	v_pk_add_f32 v[4:5], v[8:9], v[106:107]
	v_add_f32_e32 v28, v122, v28
	v_pk_mul_f32 v[8:9], v[4:5], v[4:5]
	v_add_f32_e32 v28, v123, v28
	v_pk_add_f32 v[0:1], v[10:11], v[108:109]
	v_add_f32_e32 v8, v8, v28
	v_pk_mul_f32 v[10:11], v[0:1], v[0:1]
	v_add_f32_e32 v8, v9, v8
	v_add_f32_e32 v8, v10, v8
	v_pk_mul_f32 v[64:65], v[12:13], v[12:13]
	v_add_f32_e32 v8, v11, v8
	v_add_f32_e32 v8, v64, v8
	v_pk_mul_f32 v[130:131], v[14:15], v[14:15]
	v_add_f32_e32 v8, v65, v8
	v_add_f32_e32 v8, v130, v8
	v_add_f32_e32 v10, v131, v8
	ds_bpermute_b32 v11, v232, v10
	v_lshlrev_b64 v[8:9], 11, v[210:211]
	v_lshl_add_u64 v[8:9], s[70:71], 0, v[8:9]
	s_lshl_b32 s8, s8, 1
	v_lshl_add_u64 v[8:9], v[8:9], 0, s[8:9]
	s_waitcnt lgkmcnt(0)
	v_add_f32_e32 v10, v10, v11
	v_fmamk_f32 v10, v10, 0x3c000000, v234
	v_mul_f32_e32 v11, 0x4b800000, v10
	v_cmp_gt_f32_e32 vcc, s77, v10
	v_mov_b32_e32 v213, v209
	v_lshl_add_u64 v[28:29], v[8:9], 0, v[212:213]
	v_cndmask_b32_e32 v10, v10, v11, vcc
	v_rsq_f32_e32 v10, v10
	s_mov_b64 s[34:35], 0x1b00400
	v_mul_f32_e32 v8, 0x45800000, v10
	v_cndmask_b32_e32 v8, v10, v8, vcc
	v_mul_f32_e32 v30, 0x3f4ccccd, v8
	v_pk_mul_f32 v[8:9], v[48:49], v[30:31] op_sel_hi:[1,0]
	v_pk_mul_f32 v[10:11], v[50:51], v[30:31] op_sel_hi:[1,0]
	s_waitcnt vmcnt(0)
	v_pk_mul_f32 v[8:9], v[110:111], v[8:9]
	v_pk_mul_f32 v[10:11], v[112:113], v[10:11]
	v_cvt_pk_bf16_f32 v8, v8, v9
	v_cvt_pk_bf16_f32 v9, v10, v11
	v_add_co_u32_e32 v10, vcc, s78, v28
	v_pk_mul_f32 v[48:49], v[52:53], v[30:31] op_sel_hi:[1,0]
	s_nop 0
	v_addc_co_u32_e32 v11, vcc, 0, v29, vcc
	global_store_dwordx2 v[10:11], v[8:9], off offset:1024
	v_mov_b32_e32 v8, v176
	v_mov_b32_e32 v9, v177
	v_mov_b32_e32 v10, v178
	v_mov_b32_e32 v11, v179
	v_lshl_add_u64 v[28:29], v[28:29], 0, s[34:35]
	v_pk_mul_f32 v[50:51], v[58:59], v[30:31] op_sel_hi:[1,0]
	v_pk_mul_f32 v[38:39], v[38:39], v[30:31] op_sel_hi:[1,0]
	v_pk_mul_f32 v[34:35], v[34:35], v[30:31] op_sel_hi:[1,0]
	v_pk_mul_f32 v[32:33], v[32:33], v[30:31] op_sel_hi:[1,0]
	v_pk_mul_f32 v[26:27], v[26:27], v[30:31] op_sel_hi:[1,0]
	v_pk_mul_f32 v[22:23], v[22:23], v[30:31] op_sel_hi:[1,0]
	v_pk_mul_f32 v[18:19], v[18:19], v[30:31] op_sel_hi:[1,0]
	v_pk_mul_f32 v[16:17], v[16:17], v[30:31] op_sel_hi:[1,0]
	v_pk_mul_f32 v[6:7], v[6:7], v[30:31] op_sel_hi:[1,0]
	v_pk_mul_f32 v[2:3], v[2:3], v[30:31] op_sel_hi:[1,0]
	v_pk_mul_f32 v[0:1], v[0:1], v[30:31] op_sel_hi:[1,0]
	v_pk_mul_f32 v[8:9], v[8:9], v[48:49]
	v_pk_mul_f32 v[48:49], v[54:55], v[30:31] op_sel_hi:[1,0]
	v_cvt_pk_bf16_f32 v8, v8, v9
	v_pk_mul_f32 v[10:11], v[10:11], v[48:49]
	v_pk_mul_f32 v[48:49], v[56:57], v[30:31] op_sel_hi:[1,0]
	v_cvt_pk_bf16_f32 v9, v10, v11
	global_store_dwordx2 v[28:29], v[8:9], off offset:16
	v_mov_b32_e32 v8, v180
	v_mov_b32_e32 v9, v181
	v_mov_b32_e32 v10, v182
	v_mov_b32_e32 v11, v183
	v_pk_mul_f32 v[8:9], v[8:9], v[48:49]
	v_pk_mul_f32 v[10:11], v[10:11], v[50:51]
	v_cvt_pk_bf16_f32 v8, v8, v9
	v_cvt_pk_bf16_f32 v9, v10, v11
	global_store_dwordx2 v[28:29], v[8:9], off offset:32
	v_mov_b32_e32 v8, v184
	v_mov_b32_e32 v9, v185
	v_mov_b32_e32 v10, v186
	v_mov_b32_e32 v11, v187
	v_pk_mul_f32 v[48:49], v[60:61], v[30:31] op_sel_hi:[1,0]
	v_pk_mul_f32 v[50:51], v[62:63], v[30:31] op_sel_hi:[1,0]
	v_pk_mul_f32 v[8:9], v[8:9], v[48:49]
	v_pk_mul_f32 v[10:11], v[10:11], v[50:51]
	v_cvt_pk_bf16_f32 v8, v8, v9
	v_cvt_pk_bf16_f32 v9, v10, v11
	global_store_dwordx2 v[28:29], v[8:9], off offset:48
	v_mov_b32_e32 v8, v188
	v_mov_b32_e32 v9, v189
	v_mov_b32_e32 v10, v190
	v_mov_b32_e32 v11, v191
	v_pk_mul_f32 v[48:49], v[82:83], v[30:31] op_sel_hi:[1,0]
	v_pk_mul_f32 v[50:51], v[84:85], v[30:31] op_sel_hi:[1,0]
	v_pk_mul_f32 v[8:9], v[8:9], v[48:49]
	v_pk_mul_f32 v[10:11], v[10:11], v[50:51]
	v_cvt_pk_bf16_f32 v8, v8, v9
	v_cvt_pk_bf16_f32 v9, v10, v11
	global_store_dwordx2 v[28:29], v[8:9], off offset:64
	v_mov_b32_e32 v8, v192
	v_mov_b32_e32 v9, v193
	v_mov_b32_e32 v10, v194
	v_mov_b32_e32 v11, v195
	v_pk_mul_f32 v[48:49], v[86:87], v[30:31] op_sel_hi:[1,0]
	v_pk_mul_f32 v[10:11], v[10:11], v[38:39]
	v_pk_mul_f32 v[8:9], v[8:9], v[48:49]
	v_pk_mul_f32 v[38:39], v[40:41], v[30:31] op_sel_hi:[1,0]
	v_cvt_pk_bf16_f32 v8, v8, v9
	v_cvt_pk_bf16_f32 v9, v10, v11
	global_store_dwordx2 v[28:29], v[8:9], off offset:80
	v_mov_b32_e32 v8, v196
	v_mov_b32_e32 v9, v197
	v_mov_b32_e32 v10, v198
	v_mov_b32_e32 v11, v199
	v_pk_mul_f32 v[40:41], v[42:43], v[30:31] op_sel_hi:[1,0]
	v_pk_mul_f32 v[8:9], v[8:9], v[38:39]
	v_pk_mul_f32 v[10:11], v[10:11], v[40:41]
	v_cvt_pk_bf16_f32 v8, v8, v9
	v_cvt_pk_bf16_f32 v9, v10, v11
	global_store_dwordx2 v[28:29], v[8:9], off offset:96
	v_mov_b32_e32 v8, v200
	v_mov_b32_e32 v9, v201
	v_mov_b32_e32 v10, v202
	v_mov_b32_e32 v11, v203
	v_pk_mul_f32 v[38:39], v[44:45], v[30:31] op_sel_hi:[1,0]
	v_pk_mul_f32 v[40:41], v[46:47], v[30:31] op_sel_hi:[1,0]
	v_pk_mul_f32 v[8:9], v[8:9], v[38:39]
	v_pk_mul_f32 v[10:11], v[10:11], v[40:41]
	v_cvt_pk_bf16_f32 v8, v8, v9
	v_cvt_pk_bf16_f32 v9, v10, v11
	global_store_dwordx2 v[28:29], v[8:9], off offset:112
	v_mov_b32_e32 v8, v204
	v_mov_b32_e32 v9, v205
	v_mov_b32_e32 v10, v206
	v_mov_b32_e32 v11, v207
	v_pk_mul_f32 v[38:39], v[98:99], v[30:31] op_sel_hi:[1,0]
	v_pk_mul_f32 v[10:11], v[10:11], v[34:35]
	v_pk_mul_f32 v[8:9], v[8:9], v[38:39]
	v_pk_mul_f32 v[34:35], v[36:37], v[30:31] op_sel_hi:[1,0]
	v_cvt_pk_bf16_f32 v8, v8, v9
	v_cvt_pk_bf16_f32 v9, v10, v11
	global_store_dwordx2 v[28:29], v[8:9], off offset:128
	v_mov_b32_e32 v8, v216
	v_mov_b32_e32 v9, v217
	v_mov_b32_e32 v10, v218
	v_mov_b32_e32 v11, v219
	v_pk_mul_f32 v[8:9], v[8:9], v[34:35]
	v_pk_mul_f32 v[10:11], v[10:11], v[32:33]
	v_cvt_pk_bf16_f32 v8, v8, v9
	v_cvt_pk_bf16_f32 v9, v10, v11
	global_store_dwordx2 v[28:29], v[8:9], off offset:144
	v_mov_b32_e32 v8, v220
	v_mov_b32_e32 v9, v221
	v_mov_b32_e32 v10, v222
	v_mov_b32_e32 v11, v223
	v_pk_mul_f32 v[8:9], v[8:9], v[26:27]
	v_pk_mul_f32 v[10:11], v[10:11], v[22:23]
	v_cvt_pk_bf16_f32 v8, v8, v9
	v_cvt_pk_bf16_f32 v9, v10, v11
	global_store_dwordx2 v[28:29], v[8:9], off offset:160
	v_mov_b32_e32 v8, v224
	v_mov_b32_e32 v9, v225
	v_mov_b32_e32 v10, v226
	v_mov_b32_e32 v11, v227
	v_pk_mul_f32 v[22:23], v[24:25], v[30:31] op_sel_hi:[1,0]
	v_pk_mul_f32 v[10:11], v[10:11], v[18:19]
	v_pk_mul_f32 v[8:9], v[8:9], v[22:23]
	v_pk_mul_f32 v[18:19], v[20:21], v[30:31] op_sel_hi:[1,0]
	v_cvt_pk_bf16_f32 v8, v8, v9
	v_cvt_pk_bf16_f32 v9, v10, v11
	global_store_dwordx2 v[28:29], v[8:9], off offset:176
	v_mov_b32_e32 v8, v236
	v_mov_b32_e32 v9, v237
	v_mov_b32_e32 v10, v238
	v_mov_b32_e32 v11, v239
	v_pk_mul_f32 v[8:9], v[8:9], v[18:19]
	v_pk_mul_f32 v[10:11], v[10:11], v[16:17]
	v_cvt_pk_bf16_f32 v8, v8, v9
	v_cvt_pk_bf16_f32 v9, v10, v11
	global_store_dwordx2 v[28:29], v[8:9], off offset:192
	v_mov_b32_e32 v8, v240
	v_mov_b32_e32 v9, v241
	v_mov_b32_e32 v10, v242
	v_mov_b32_e32 v11, v243
	v_pk_mul_f32 v[6:7], v[8:9], v[6:7]
	v_pk_mul_f32 v[2:3], v[10:11], v[2:3]
	v_cvt_pk_bf16_f32 v6, v6, v7
	v_cvt_pk_bf16_f32 v7, v2, v3
	global_store_dwordx2 v[28:29], v[6:7], off offset:208
	v_mov_b32_e32 v6, v244
	v_mov_b32_e32 v7, v245
	v_mov_b32_e32 v8, v246
	v_mov_b32_e32 v9, v247
	v_pk_mul_f32 v[2:3], v[4:5], v[30:31] op_sel_hi:[1,0]
	v_pk_mul_f32 v[4:5], v[12:13], v[30:31] op_sel_hi:[1,0]
	v_pk_mul_f32 v[2:3], v[6:7], v[2:3]
	v_pk_mul_f32 v[0:1], v[8:9], v[0:1]
	v_cvt_pk_bf16_f32 v2, v2, v3
	v_cvt_pk_bf16_f32 v3, v0, v1
	global_store_dwordx2 v[28:29], v[2:3], off offset:224
	v_mov_b32_e32 v0, v248
	v_mov_b32_e32 v1, v249
	v_mov_b32_e32 v2, v250
	v_mov_b32_e32 v3, v251
	v_pk_mul_f32 v[6:7], v[14:15], v[30:31] op_sel_hi:[1,0]
	v_pk_mul_f32 v[0:1], v[0:1], v[4:5]
	v_pk_mul_f32 v[2:3], v[2:3], v[6:7]
	v_cvt_pk_bf16_f32 v0, v0, v1
	v_cvt_pk_bf16_f32 v1, v2, v3
	global_store_dwordx2 v[28:29], v[0:1], off offset:240
	s_branch .LBB0_577

.LBB0_1525:
	s_or_b64 exec, exec, s[4:5]
	v_cmp_gt_u32_e32 vcc, s0, v205
	s_waitcnt lgkmcnt(0)
	s_barrier
	s_and_saveexec_b64 s[40:41], vcc
	s_cbranch_execz .LBB0_1505
	ds_read_b128 v[66:69], v64
	ds_read_b128 v[70:73], v64 offset:32
	ds_read_b128 v[74:77], v64 offset:64
	ds_read_b128 v[78:81], v64 offset:96
	ds_read_b128 v[82:85], v64 offset:128
	ds_read_b128 v[86:89], v64 offset:160
	ds_read_b128 v[90:93], v64 offset:192
	ds_read_b128 v[94:97], v64 offset:224
	ds_read_b128 v[98:101], v64 offset:256
	ds_read_b128 v[102:105], v64 offset:288
	ds_read_b128 v[106:109], v64 offset:448
	ds_read_b128 v[110:113], v64 offset:480
	ds_read_b128 v[114:117], v64 offset:320
	ds_read_b128 v[118:121], v64 offset:352
	ds_read_b128 v[122:125], v64 offset:384
	ds_read_b128 v[126:129], v64 offset:416
	s_waitcnt lgkmcnt(14)
	v_pk_add_f32 v[48:49], v[48:49], v[66:67]
	v_pk_add_f32 v[50:51], v[50:51], v[68:69]
	v_pk_mul_f32 v[66:67], v[48:49], v[48:49]
	s_waitcnt lgkmcnt(4)
	v_pk_add_f32 v[12:13], v[12:13], v[110:111]
	v_pk_add_f32 v[14:15], v[14:15], v[112:113]
	global_load_dwordx4 v[110:113], v200, s[46:47] offset:512
	global_load_dwordx4 v[172:175], v200, s[46:47] offset:544
	global_load_dwordx4 v[176:179], v200, s[46:47] offset:576
	global_load_dwordx4 v[180:183], v200, s[46:47] offset:608
	global_load_dwordx4 v[184:187], v200, s[46:47] offset:640
	global_load_dwordx4 v[188:191], v200, s[46:47] offset:672
	global_load_dwordx4 v[192:195], v200, s[46:47] offset:704
	global_load_dwordx4 v[196:199], v200, s[46:47] offset:736
	global_load_dwordx4 v[208:211], v200, s[46:47] offset:768
	global_load_dwordx4 v[212:215], v200, s[46:47] offset:800
	global_load_dwordx4 v[216:219], v200, s[46:47] offset:832
	global_load_dwordx4 v[232:235], v200, s[46:47] offset:864
	global_load_dwordx4 v[236:239], v200, s[46:47] offset:896
	global_load_dwordx4 v[240:243], v200, s[46:47] offset:928
	global_load_dwordx4 v[244:247], v200, s[46:47] offset:960
	global_load_dwordx4 v[248:251], v200, s[46:47] offset:992
	v_pk_mul_f32 v[68:69], v[50:51], v[50:51]
	v_add_f32_e32 v66, v66, v67
	v_pk_add_f32 v[52:53], v[52:53], v[70:71]
	v_add_f32_e32 v66, v68, v66
	v_pk_mul_f32 v[70:71], v[52:53], v[52:53]
	v_add_f32_e32 v66, v69, v66
	v_pk_add_f32 v[54:55], v[54:55], v[72:73]
	v_add_f32_e32 v66, v70, v66
	v_pk_mul_f32 v[72:73], v[54:55], v[54:55]
	v_add_f32_e32 v66, v71, v66
	v_pk_add_f32 v[56:57], v[56:57], v[74:75]
	v_add_f32_e32 v66, v72, v66
	v_pk_mul_f32 v[74:75], v[56:57], v[56:57]
	v_add_f32_e32 v66, v73, v66
	v_pk_add_f32 v[58:59], v[58:59], v[76:77]
	v_add_f32_e32 v66, v74, v66
	v_pk_mul_f32 v[76:77], v[58:59], v[58:59]
	v_add_f32_e32 v66, v75, v66
	v_pk_add_f32 v[60:61], v[60:61], v[78:79]
	v_add_f32_e32 v66, v76, v66
	v_pk_mul_f32 v[78:79], v[60:61], v[60:61]
	v_add_f32_e32 v66, v77, v66
	v_pk_add_f32 v[62:63], v[62:63], v[80:81]
	v_add_f32_e32 v66, v78, v66
	v_pk_mul_f32 v[80:81], v[62:63], v[62:63]
	v_add_f32_e32 v66, v79, v66
	v_pk_add_f32 v[82:83], v[32:33], v[82:83]
	v_add_f32_e32 v66, v80, v66
	v_pk_mul_f32 v[134:135], v[82:83], v[82:83]
	v_add_f32_e32 v66, v81, v66
	v_pk_add_f32 v[84:85], v[34:35], v[84:85]
	v_add_f32_e32 v66, v134, v66
	v_pk_mul_f32 v[132:133], v[84:85], v[84:85]
	v_add_f32_e32 v66, v135, v66
	v_pk_add_f32 v[86:87], v[36:37], v[86:87]
	v_add_f32_e32 v66, v132, v66
	v_pk_mul_f32 v[136:137], v[86:87], v[86:87]
	v_add_f32_e32 v66, v133, v66
	v_pk_add_f32 v[38:39], v[38:39], v[88:89]
	v_add_f32_e32 v66, v136, v66
	v_pk_mul_f32 v[88:89], v[38:39], v[38:39]
	v_add_f32_e32 v66, v137, v66
	v_pk_add_f32 v[40:41], v[40:41], v[90:91]
	v_add_f32_e32 v66, v88, v66
	v_pk_mul_f32 v[90:91], v[40:41], v[40:41]
	v_add_f32_e32 v66, v89, v66
	v_pk_add_f32 v[42:43], v[42:43], v[92:93]
	v_add_f32_e32 v66, v90, v66
	v_pk_mul_f32 v[92:93], v[42:43], v[42:43]
	v_add_f32_e32 v66, v91, v66
	v_pk_add_f32 v[44:45], v[44:45], v[94:95]
	v_add_f32_e32 v66, v92, v66
	v_pk_mul_f32 v[94:95], v[44:45], v[44:45]
	v_add_f32_e32 v66, v93, v66
	v_pk_add_f32 v[46:47], v[46:47], v[96:97]
	v_add_f32_e32 v66, v94, v66
	v_pk_mul_f32 v[96:97], v[46:47], v[46:47]
	v_add_f32_e32 v66, v95, v66
	v_pk_add_f32 v[98:99], v[16:17], v[98:99]
	v_add_f32_e32 v66, v96, v66
	v_pk_mul_f32 v[138:139], v[98:99], v[98:99]
	v_add_f32_e32 v66, v97, v66
	v_pk_add_f32 v[34:35], v[18:19], v[100:101]
	v_add_f32_e32 v66, v138, v66
	v_pk_mul_f32 v[100:101], v[34:35], v[34:35]
	v_add_f32_e32 v66, v139, v66
	v_pk_add_f32 v[36:37], v[20:21], v[102:103]
	v_add_f32_e32 v66, v100, v66
	v_pk_mul_f32 v[102:103], v[36:37], v[36:37]
	v_add_f32_e32 v66, v101, v66
	v_pk_add_f32 v[32:33], v[22:23], v[104:105]
	v_add_f32_e32 v66, v102, v66
	v_pk_mul_f32 v[104:105], v[32:33], v[32:33]
	v_add_f32_e32 v66, v103, v66
	s_waitcnt lgkmcnt(3)
	v_pk_add_f32 v[22:23], v[26:27], v[116:117]
	v_pk_add_f32 v[26:27], v[24:25], v[114:115]
	v_add_f32_e32 v66, v104, v66
	v_pk_mul_f32 v[114:115], v[26:27], v[26:27]
	v_add_f32_e32 v66, v105, v66
	v_add_f32_e32 v66, v114, v66
	v_pk_mul_f32 v[116:117], v[22:23], v[22:23]
	v_add_f32_e32 v66, v115, v66
	s_waitcnt lgkmcnt(2)
	v_pk_add_f32 v[24:25], v[28:29], v[118:119]
	v_add_f32_e32 v66, v116, v66
	v_pk_mul_f32 v[28:29], v[24:25], v[24:25]
	v_add_f32_e32 v66, v117, v66
	v_pk_add_f32 v[18:19], v[30:31], v[120:121]
	v_add_f32_e32 v28, v28, v66
	v_pk_mul_f32 v[30:31], v[18:19], v[18:19]
	v_add_f32_e32 v28, v29, v28
	s_waitcnt lgkmcnt(1)
	v_pk_add_f32 v[20:21], v[0:1], v[122:123]
	v_add_f32_e32 v28, v30, v28
	v_pk_mul_f32 v[120:121], v[20:21], v[20:21]
	v_add_f32_e32 v28, v31, v28
	v_pk_add_f32 v[16:17], v[2:3], v[124:125]
	v_add_f32_e32 v28, v120, v28
	v_pk_mul_f32 v[118:119], v[16:17], v[16:17]
	v_add_f32_e32 v28, v121, v28
	s_waitcnt lgkmcnt(0)
	v_pk_add_f32 v[2:3], v[6:7], v[128:129]
	v_pk_add_f32 v[6:7], v[4:5], v[126:127]
	v_add_f32_e32 v28, v118, v28
	v_pk_mul_f32 v[124:125], v[6:7], v[6:7]
	v_add_f32_e32 v28, v119, v28
	v_add_f32_e32 v28, v124, v28
	v_pk_mul_f32 v[122:123], v[2:3], v[2:3]
	v_add_f32_e32 v28, v125, v28
	v_pk_add_f32 v[4:5], v[8:9], v[106:107]
	v_add_f32_e32 v28, v122, v28
	v_pk_mul_f32 v[8:9], v[4:5], v[4:5]
	v_add_f32_e32 v28, v123, v28
	v_pk_add_f32 v[0:1], v[10:11], v[108:109]
	v_add_f32_e32 v8, v8, v28
	v_pk_mul_f32 v[10:11], v[0:1], v[0:1]
	v_add_f32_e32 v8, v9, v8
	v_add_f32_e32 v8, v10, v8
	v_pk_mul_f32 v[64:65], v[12:13], v[12:13]
	v_add_f32_e32 v8, v11, v8
	v_add_f32_e32 v8, v64, v8
	v_pk_mul_f32 v[130:131], v[14:15], v[14:15]
	v_add_f32_e32 v8, v65, v8
	v_add_f32_e32 v8, v130, v8
	v_add_f32_e32 v10, v131, v8
	ds_bpermute_b32 v11, v223, v10
	v_lshlrev_b64 v[8:9], 11, v[202:203]
	v_lshl_add_u64 v[8:9], s[70:71], 0, v[8:9]
	s_lshl_b32 s12, s12, 1
	v_lshl_add_u64 v[8:9], v[8:9], 0, s[12:13]
	s_waitcnt lgkmcnt(0)
	v_add_f32_e32 v10, v10, v11
	v_fmamk_f32 v10, v10, 0x3c000000, v225
	v_mul_f32_e32 v11, 0x4b800000, v10
	v_cmp_gt_f32_e32 vcc, s54, v10
	v_mov_b32_e32 v205, v201
	v_lshl_add_u64 v[28:29], v[8:9], 0, v[204:205]
	v_cndmask_b32_e32 v10, v10, v11, vcc
	v_rsq_f32_e32 v10, v10
	s_nop 0
	v_mul_f32_e32 v8, 0x45800000, v10
	v_cndmask_b32_e32 v8, v10, v8, vcc
	v_mul_f32_e32 v30, 0x3f24fd5c, v8
	v_pk_mul_f32 v[8:9], v[48:49], v[30:31] op_sel_hi:[1,0]
	v_pk_mul_f32 v[10:11], v[50:51], v[30:31] op_sel_hi:[1,0]
	s_waitcnt vmcnt(0)
	v_pk_mul_f32 v[8:9], v[110:111], v[8:9]
	v_pk_mul_f32 v[10:11], v[112:113], v[10:11]
	v_cvt_pk_bf16_f32 v8, v8, v9
	v_cvt_pk_bf16_f32 v9, v10, v11
	v_add_co_u32_e32 v10, vcc, s55, v28
	v_pk_mul_f32 v[48:49], v[52:53], v[30:31] op_sel_hi:[1,0]
	s_nop 0
	v_addc_co_u32_e32 v11, vcc, 0, v29, vcc
	global_store_dwordx2 v[10:11], v[8:9], off offset:1024
	v_mov_b32_e32 v8, v172
	v_mov_b32_e32 v9, v173
	v_mov_b32_e32 v10, v174
	v_mov_b32_e32 v11, v175
	v_lshl_add_u64 v[28:29], v[28:29], 0, s[24:25]
	v_pk_mul_f32 v[50:51], v[58:59], v[30:31] op_sel_hi:[1,0]
	v_pk_mul_f32 v[38:39], v[38:39], v[30:31] op_sel_hi:[1,0]
	v_pk_mul_f32 v[34:35], v[34:35], v[30:31] op_sel_hi:[1,0]
	v_pk_mul_f32 v[32:33], v[32:33], v[30:31] op_sel_hi:[1,0]
	v_pk_mul_f32 v[26:27], v[26:27], v[30:31] op_sel_hi:[1,0]
	v_pk_mul_f32 v[22:23], v[22:23], v[30:31] op_sel_hi:[1,0]
	v_pk_mul_f32 v[18:19], v[18:19], v[30:31] op_sel_hi:[1,0]
	v_pk_mul_f32 v[16:17], v[16:17], v[30:31] op_sel_hi:[1,0]
	v_pk_mul_f32 v[6:7], v[6:7], v[30:31] op_sel_hi:[1,0]
	v_pk_mul_f32 v[2:3], v[2:3], v[30:31] op_sel_hi:[1,0]
	v_pk_mul_f32 v[0:1], v[0:1], v[30:31] op_sel_hi:[1,0]
	v_pk_mul_f32 v[8:9], v[8:9], v[48:49]
	v_pk_mul_f32 v[48:49], v[54:55], v[30:31] op_sel_hi:[1,0]
	v_cvt_pk_bf16_f32 v8, v8, v9
	v_pk_mul_f32 v[10:11], v[10:11], v[48:49]
	v_pk_mul_f32 v[48:49], v[56:57], v[30:31] op_sel_hi:[1,0]
	v_cvt_pk_bf16_f32 v9, v10, v11
	global_store_dwordx2 v[28:29], v[8:9], off offset:16
	v_mov_b32_e32 v8, v176
	v_mov_b32_e32 v9, v177
	v_mov_b32_e32 v10, v178
	v_mov_b32_e32 v11, v179
	v_pk_mul_f32 v[8:9], v[8:9], v[48:49]
	v_pk_mul_f32 v[10:11], v[10:11], v[50:51]
	v_cvt_pk_bf16_f32 v8, v8, v9
	v_cvt_pk_bf16_f32 v9, v10, v11
	global_store_dwordx2 v[28:29], v[8:9], off offset:32
	v_mov_b32_e32 v8, v180
	v_mov_b32_e32 v9, v181
	v_mov_b32_e32 v10, v182
	v_mov_b32_e32 v11, v183
	v_pk_mul_f32 v[48:49], v[60:61], v[30:31] op_sel_hi:[1,0]
	v_pk_mul_f32 v[50:51], v[62:63], v[30:31] op_sel_hi:[1,0]
	v_pk_mul_f32 v[8:9], v[8:9], v[48:49]
	v_pk_mul_f32 v[10:11], v[10:11], v[50:51]
	v_cvt_pk_bf16_f32 v8, v8, v9
	v_cvt_pk_bf16_f32 v9, v10, v11
	global_store_dwordx2 v[28:29], v[8:9], off offset:48
	v_mov_b32_e32 v8, v184
	v_mov_b32_e32 v9, v185
	v_mov_b32_e32 v10, v186
	v_mov_b32_e32 v11, v187
	v_pk_mul_f32 v[48:49], v[82:83], v[30:31] op_sel_hi:[1,0]
	v_pk_mul_f32 v[50:51], v[84:85], v[30:31] op_sel_hi:[1,0]
	v_pk_mul_f32 v[8:9], v[8:9], v[48:49]
	v_pk_mul_f32 v[10:11], v[10:11], v[50:51]
	v_cvt_pk_bf16_f32 v8, v8, v9
	v_cvt_pk_bf16_f32 v9, v10, v11
	global_store_dwordx2 v[28:29], v[8:9], off offset:64
	v_mov_b32_e32 v8, v188
	v_mov_b32_e32 v9, v189
	v_mov_b32_e32 v10, v190
	v_mov_b32_e32 v11, v191
	v_pk_mul_f32 v[48:49], v[86:87], v[30:31] op_sel_hi:[1,0]
	v_pk_mul_f32 v[10:11], v[10:11], v[38:39]
	v_pk_mul_f32 v[8:9], v[8:9], v[48:49]
	v_pk_mul_f32 v[38:39], v[40:41], v[30:31] op_sel_hi:[1,0]
	v_cvt_pk_bf16_f32 v8, v8, v9
	v_cvt_pk_bf16_f32 v9, v10, v11
	global_store_dwordx2 v[28:29], v[8:9], off offset:80
	v_mov_b32_e32 v8, v192
	v_mov_b32_e32 v9, v193
	v_mov_b32_e32 v10, v194
	v_mov_b32_e32 v11, v195
	v_pk_mul_f32 v[40:41], v[42:43], v[30:31] op_sel_hi:[1,0]
	v_pk_mul_f32 v[8:9], v[8:9], v[38:39]
	v_pk_mul_f32 v[10:11], v[10:11], v[40:41]
	v_cvt_pk_bf16_f32 v8, v8, v9
	v_cvt_pk_bf16_f32 v9, v10, v11
	global_store_dwordx2 v[28:29], v[8:9], off offset:96
	v_mov_b32_e32 v8, v196
	v_mov_b32_e32 v9, v197
	v_mov_b32_e32 v10, v198
	v_mov_b32_e32 v11, v199
	v_pk_mul_f32 v[38:39], v[44:45], v[30:31] op_sel_hi:[1,0]
	v_pk_mul_f32 v[40:41], v[46:47], v[30:31] op_sel_hi:[1,0]
	v_pk_mul_f32 v[8:9], v[8:9], v[38:39]
	v_pk_mul_f32 v[10:11], v[10:11], v[40:41]
	v_cvt_pk_bf16_f32 v8, v8, v9
	v_cvt_pk_bf16_f32 v9, v10, v11
	global_store_dwordx2 v[28:29], v[8:9], off offset:112
	v_mov_b32_e32 v8, v208
	v_mov_b32_e32 v9, v209
	v_mov_b32_e32 v10, v210
	v_mov_b32_e32 v11, v211
	v_pk_mul_f32 v[38:39], v[98:99], v[30:31] op_sel_hi:[1,0]
	v_pk_mul_f32 v[10:11], v[10:11], v[34:35]
	v_pk_mul_f32 v[8:9], v[8:9], v[38:39]
	v_pk_mul_f32 v[34:35], v[36:37], v[30:31] op_sel_hi:[1,0]
	v_cvt_pk_bf16_f32 v8, v8, v9
	v_cvt_pk_bf16_f32 v9, v10, v11
	global_store_dwordx2 v[28:29], v[8:9], off offset:128
	v_mov_b32_e32 v8, v212
	v_mov_b32_e32 v9, v213
	v_mov_b32_e32 v10, v214
	v_mov_b32_e32 v11, v215
	v_pk_mul_f32 v[8:9], v[8:9], v[34:35]
	v_pk_mul_f32 v[10:11], v[10:11], v[32:33]
	v_cvt_pk_bf16_f32 v8, v8, v9
	v_cvt_pk_bf16_f32 v9, v10, v11
	global_store_dwordx2 v[28:29], v[8:9], off offset:144
	v_mov_b32_e32 v8, v216
	v_mov_b32_e32 v9, v217
	v_mov_b32_e32 v10, v218
	v_mov_b32_e32 v11, v219
	v_pk_mul_f32 v[8:9], v[8:9], v[26:27]
	v_pk_mul_f32 v[10:11], v[10:11], v[22:23]
	v_cvt_pk_bf16_f32 v8, v8, v9
	v_cvt_pk_bf16_f32 v9, v10, v11
	global_store_dwordx2 v[28:29], v[8:9], off offset:160
	v_mov_b32_e32 v8, v232
	v_mov_b32_e32 v9, v233
	v_mov_b32_e32 v10, v234
	v_mov_b32_e32 v11, v235
	v_pk_mul_f32 v[22:23], v[24:25], v[30:31] op_sel_hi:[1,0]
	v_pk_mul_f32 v[10:11], v[10:11], v[18:19]
	v_pk_mul_f32 v[8:9], v[8:9], v[22:23]
	v_pk_mul_f32 v[18:19], v[20:21], v[30:31] op_sel_hi:[1,0]
	v_cvt_pk_bf16_f32 v8, v8, v9
	v_cvt_pk_bf16_f32 v9, v10, v11
	global_store_dwordx2 v[28:29], v[8:9], off offset:176
	v_mov_b32_e32 v8, v236
	v_mov_b32_e32 v9, v237
	v_mov_b32_e32 v10, v238
	v_mov_b32_e32 v11, v239
	v_pk_mul_f32 v[8:9], v[8:9], v[18:19]
	v_pk_mul_f32 v[10:11], v[10:11], v[16:17]
	v_cvt_pk_bf16_f32 v8, v8, v9
	v_cvt_pk_bf16_f32 v9, v10, v11
	global_store_dwordx2 v[28:29], v[8:9], off offset:192
	v_mov_b32_e32 v8, v240
	v_mov_b32_e32 v9, v241
	v_mov_b32_e32 v10, v242
	v_mov_b32_e32 v11, v243
	v_pk_mul_f32 v[6:7], v[8:9], v[6:7]
	v_pk_mul_f32 v[2:3], v[10:11], v[2:3]
	v_cvt_pk_bf16_f32 v6, v6, v7
	v_cvt_pk_bf16_f32 v7, v2, v3
	global_store_dwordx2 v[28:29], v[6:7], off offset:208
	v_mov_b32_e32 v6, v244
	v_mov_b32_e32 v7, v245
	v_mov_b32_e32 v8, v246
	v_mov_b32_e32 v9, v247
	v_pk_mul_f32 v[2:3], v[4:5], v[30:31] op_sel_hi:[1,0]
	v_pk_mul_f32 v[4:5], v[12:13], v[30:31] op_sel_hi:[1,0]
	v_pk_mul_f32 v[2:3], v[6:7], v[2:3]
	v_pk_mul_f32 v[0:1], v[8:9], v[0:1]
	v_cvt_pk_bf16_f32 v2, v2, v3
	v_cvt_pk_bf16_f32 v3, v0, v1
	global_store_dwordx2 v[28:29], v[2:3], off offset:224
	v_mov_b32_e32 v0, v248
	v_mov_b32_e32 v1, v249
	v_mov_b32_e32 v2, v250
	v_mov_b32_e32 v3, v251
	v_pk_mul_f32 v[6:7], v[14:15], v[30:31] op_sel_hi:[1,0]
	v_pk_mul_f32 v[0:1], v[0:1], v[4:5]
	v_pk_mul_f32 v[2:3], v[2:3], v[6:7]
	v_cvt_pk_bf16_f32 v0, v0, v1
	v_cvt_pk_bf16_f32 v1, v2, v3
	global_store_dwordx2 v[28:29], v[0:1], off offset:240
	s_branch .LBB0_1505
